# attention ping-pong loops: deferred cvt/rowsum in PV gaps, long-lead LDS prefetch, B first MFMA right after barrier, equal MFMA-phase priority; metadata sgpr_count updated
# baseline (speedup 1.0000x reference)
; __global__ void __launch_bounds__(NTHR) fwd_megakernel(Params p) {
;   extern __shared__ __attribute__((aligned(16))) unsigned char smem[];
amdhsa.kernels:
  - .agpr_count:     0
    .args:
      - .offset:         0
        .size:           328
        .value_kind:     by_value
      - .offset:         328
        .size:           4
        .value_kind:     hidden_block_count_x
      - .offset:         332
        .size:           4
        .value_kind:     hidden_block_count_y
      - .offset:         336
        .size:           4
        .value_kind:     hidden_block_count_z
      - .offset:         340
        .size:           2
        .value_kind:     hidden_group_size_x
      - .offset:         342
        .size:           2
        .value_kind:     hidden_group_size_y
      - .offset:         344
        .size:           2
        .value_kind:     hidden_group_size_z
      - .offset:         346
        .size:           2
        .value_kind:     hidden_remainder_x
      - .offset:         348
        .size:           2
        .value_kind:     hidden_remainder_y
      - .offset:         350
        .size:           2
        .value_kind:     hidden_remainder_z
      - .offset:         368
        .size:           8
        .value_kind:     hidden_global_offset_x
      - .offset:         376
        .size:           8
        .value_kind:     hidden_global_offset_y
      - .offset:         384
        .size:           8
        .value_kind:     hidden_global_offset_z
      - .offset:         392
        .size:           2
        .value_kind:     hidden_grid_dims
      - .offset:         416
        .size:           8
        .value_kind:     hidden_multigrid_sync_arg
      - .offset:         448
        .size:           4
        .value_kind:     hidden_dynamic_lds_size
    .group_segment_fixed_size: 0
    .kernarg_segment_align: 8
    .kernarg_segment_size: 584
    .language:       OpenCL C
    .language_version:
      - 2
      - 0
    .max_flat_workgroup_size: 512
    .name:           _Z14fwd_megakernel6Params
    .private_segment_fixed_size: 0
    .sgpr_count:     108
    .sgpr_spill_count: 100
    .symbol:         _Z14fwd_megakernel6Params.kd
    .uniform_work_group_size: 1
    .uses_dynamic_stack: false
    .vgpr_count:     256
    .vgpr_spill_count: 0
    .wavefront_size: 64
